# speedup vs baseline: 1.0036x; 1.0023x over previous
; __device__ __forceinline__ void dn_prep_unit(int layer, int sample, int b, int n, int h, unsigned char* shm) {
;     ...
;     for (int bi = 0; bi < 4; ++bi) {
;         if (bi > 0) {
; #pragma unroll
;             for (int q = 0; q < 2; ++q) { const int n0 = (wid * 2 + q) * 16;
;                 f32x4 acc;
; #pragma unroll
;                 for (int j = 0; j < 4; ++j) acc[j] = RHS[(bi * 16 + fq * 4 + j) * 260 + n0 + fr];
;                 for (int k0 = 0; k0 < bi * 16; k0 += 4) { const float a_ = -Lm[(bi * 16 + fr) * 68 + k0 + fq], b_ = RHS[(k0 + fq) * 260 + n0 + fr];
;                     acc = __builtin_amdgcn_mfma_f32_16x16x4f32(a_, b_, acc, 0, 0, 0); }
; #pragma unroll
;                 for (int j = 0; j < 4; ++j) RHS[(bi * 16 + fq * 4 + j) * 260 + n0 + fr] = acc[j]; }
;             __syncthreads();
.LBB0_1080:
	s_cmp_eq_u32 s18, 0
	s_cbranch_scc1 .LBB0_1086
	s_lshl_b32 s6, s18, 4
	v_or_b32_e32 v2, s6, v147
	v_mul_lo_u32 v2, v2, s59
	v_add_u32_e32 v6, v153, v2
	ds_read_b32 v2, v6 offset:512
	ds_read_b32 v3, v6 offset:1552
	ds_read_b32 v4, v6 offset:2592
	ds_read_b32 v5, v6 offset:3632
	ds_read_b32 v196, v6 offset:576
	ds_read_b32 v197, v6 offset:1616
	ds_read_b32 v198, v6 offset:2656
	ds_read_b32 v199, v6 offset:3696
	s_mov_b32 s7, 0
	v_mov_b32_e32 v7, v155
	v_mov_b32_e32 v8, v154
	v_mov_b32_e32 v9, v156
.Lfs_loop:
	ds_read_b32 v184, v7
	ds_read_b32 v188, v8
	ds_read_b32 v192, v9
	ds_read_b32 v185, v7 offset:16
	ds_read_b32 v189, v8 offset:4160
	ds_read_b32 v193, v9 offset:4160
	ds_read_b32 v186, v7 offset:32
	ds_read_b32 v190, v8 offset:8320
	ds_read_b32 v194, v9 offset:8320
	ds_read_b32 v187, v7 offset:48
	ds_read_b32 v191, v8 offset:12480
	ds_read_b32 v195, v9 offset:12480
	s_add_i32 s7, s7, 16
	v_add_u32_e32 v7, 64, v7
	v_add_u32_e32 v8, 0x4100, v8
	v_add_u32_e32 v9, 0x4100, v9
	s_waitcnt lgkmcnt(9)
	v_xor_b32_e32 v184, 0x80000000, v184
	s_cmp_ge_u32 s7, s6
	s_nop 0
	v_mfma_f32_16x16x4_f32 v[2:5], v184, v188, v[2:5]
	v_mfma_f32_16x16x4_f32 v[196:199], v184, v192, v[196:199]
	s_waitcnt lgkmcnt(6)
	v_xor_b32_e32 v185, 0x80000000, v185
	s_nop 1
	v_mfma_f32_16x16x4_f32 v[2:5], v185, v189, v[2:5]
	v_mfma_f32_16x16x4_f32 v[196:199], v185, v193, v[196:199]
	s_waitcnt lgkmcnt(3)
	v_xor_b32_e32 v186, 0x80000000, v186
	s_nop 1
	v_mfma_f32_16x16x4_f32 v[2:5], v186, v190, v[2:5]
	v_mfma_f32_16x16x4_f32 v[196:199], v186, v194, v[196:199]
	s_waitcnt lgkmcnt(0)
	v_xor_b32_e32 v187, 0x80000000, v187
	s_nop 1
	v_mfma_f32_16x16x4_f32 v[2:5], v187, v191, v[2:5]
	v_mfma_f32_16x16x4_f32 v[196:199], v187, v195, v[196:199]
	s_cbranch_scc0 .Lfs_loop
	s_nop 9
	ds_write_b32 v6, v2 offset:512
	ds_write_b32 v6, v3 offset:1552
	ds_write_b32 v6, v4 offset:2592
	ds_write_b32 v6, v5 offset:3632
	s_nop 1
	ds_write_b32 v6, v196 offset:576
	ds_write_b32 v6, v197 offset:1616
	ds_write_b32 v6, v198 offset:2656
	ds_write_b32 v6, v199 offset:3696
	s_waitcnt lgkmcnt(0)
	s_barrier
